# SwiGLU epilogue: store addresses as 32-bit v_mad_u32_u24 offsets on an SGPR base instead of v_mad_i64_i32 + 64-bit adds per row group (on top of attention VALU diet)
# baseline (speedup 1.0000x reference)
; __device__ __forceinline__ u32x4 pack8(f32x4 a, f32x4 b) { u32x4 w; w.x = cvt_pk_bf16(a[0], a[1]); w.y = cvt_pk_bf16(a[2], a[3]); w.z = cvt_pk_bf16(b[0], b[1]); w.w = cvt_pk_bf16(b[2], b[3]); return w; }
;     __device__ __forceinline__ void operator()(const f32x4 (&acc)[2][2][4][2], const Unit& u, int wr, int wc, int fr, int fq) const {
;         const int rl0 = wr * 64 + fr, col0 = u.pn * HALF + wc * 32 + 8 * fq;
; #pragma unroll
;         for (int ai = 0; ai < 2; ++ai)
; #pragma unroll
;             for (int m = 0; m < 4; ++m) { const int rl = rl0 + ai * HALF + m * 16; const float s = rs[u.ui * BM + rl];
;                 f32x4 h[2]; const float ns = -1.4426950408889634f * s, s2 = s * s;
; #pragma unroll
;                 for (int n = 0; n < 2; ++n) { const f32x4 g = acc[ai][0][m][n], up = acc[ai][1][m][n]; const f32x4 ea = g * ns;
;                     const f32x4 d = (f32x4){__builtin_amdgcn_exp2f(ea[0]), __builtin_amdgcn_exp2f(ea[1]), __builtin_amdgcn_exp2f(ea[2]), __builtin_amdgcn_exp2f(ea[3])} + 1.0f;
;                     const f32x4 r = (f32x4){__builtin_amdgcn_rcpf(d[0]), __builtin_amdgcn_rcpf(d[1]), __builtin_amdgcn_rcpf(d[2]), __builtin_amdgcn_rcpf(d[3])};
;                     h[n] = (g * up) * (r * s2); }
;                 st16(O + (size_t)(u.pm * BM + rl) * ldo + col0, pack8(h[0], h[1])); }
.LBB0_372:
	v_lshl_add_u32 v150, s35, 10, v148
	ds_read_b32 v151, v150
	v_pk_mul_f32 v[122:123], v[126:127], v[122:123]
	v_pk_mul_f32 v[120:121], v[124:125], v[120:121]
	v_pk_mul_f32 v[114:115], v[118:119], v[114:115]
	v_pk_mul_f32 v[112:113], v[116:117], v[112:113]
	s_waitcnt lgkmcnt(0)
	v_mul_f32_e32 v154, 0xbfb8aa3b, v151
	v_pk_mul_f32 v[156:157], v[126:127], v[154:155] op_sel_hi:[1,0]
	v_pk_mul_f32 v[158:159], v[124:125], v[154:155] op_sel_hi:[1,0]
	v_exp_f32_e32 v156, v156
	v_exp_f32_e32 v157, v157
	v_exp_f32_e32 v158, v158
	v_exp_f32_e32 v159, v159
	v_mul_f32_e32 v160, v151, v151
	v_pk_add_f32 v[156:157], v[156:157], 1.0 op_sel_hi:[1,0]
	s_lshl_b32 s14, s66, 8
	v_rcp_f32_e32 v156, v156
	v_rcp_f32_e32 v157, v157
	v_pk_add_f32 v[158:159], v[158:159], 1.0 op_sel_hi:[1,0]
	v_lshl_or_b32 v152, s31, 7, v147
	v_rcp_f32_e32 v158, v158
	v_rcp_f32_e32 v159, v159
	v_pk_mul_f32 v[126:127], v[160:161], v[156:157] op_sel_hi:[0,1]
	v_pk_mul_f32 v[156:157], v[118:119], v[154:155] op_sel_hi:[1,0]
	v_pk_mul_f32 v[154:155], v[116:117], v[154:155] op_sel_hi:[1,0]
	v_exp_f32_e32 v156, v156
	v_exp_f32_e32 v154, v154
	v_exp_f32_e32 v157, v157
	v_exp_f32_e32 v155, v155
	v_pk_mul_f32 v[124:125], v[160:161], v[158:159] op_sel_hi:[0,1]
	v_pk_mul_f32 v[122:123], v[122:123], v[126:127]
	v_pk_mul_f32 v[120:121], v[120:121], v[124:125]
	v_pk_add_f32 v[124:125], v[156:157], 1.0 op_sel_hi:[1,0]
	v_pk_add_f32 v[126:127], v[154:155], 1.0 op_sel_hi:[1,0]
	v_rcp_f32_e32 v124, v124
	v_rcp_f32_e32 v126, v126
	v_rcp_f32_e32 v127, v127
	v_rcp_f32_e32 v125, v125
	v_pk_mul_f32 v[106:107], v[110:111], v[106:107]
	v_pk_mul_f32 v[116:117], v[160:161], v[126:127] op_sel_hi:[0,1]
	v_pk_mul_f32 v[118:119], v[160:161], v[124:125] op_sel_hi:[0,1]
	v_pk_mul_f32 v[114:115], v[114:115], v[118:119]
	v_pk_mul_f32 v[118:119], v[112:113], v[116:117]
	v_cvt_pk_bf16_f32 v116, v120, v121
	v_cvt_pk_bf16_f32 v117, v122, v123
	v_add_u32_e32 v124, s14, v138
	v_cvt_pk_bf16_f32 v118, v118, v119
	v_cvt_pk_bf16_f32 v119, v114, v115
	ds_read_b32 v123, v150 offset:64
	v_lshlrev_b32_e32 v114, 1, v152
	v_mad_u32_u24 v120, v124, s5, v114
	s_waitcnt lgkmcnt(0)
	v_mul_f32_e32 v122, 0xbfb8aa3b, v123
	v_pk_mul_f32 v[124:125], v[110:111], v[122:123] op_sel_hi:[1,0]
	v_pk_mul_f32 v[126:127], v[108:109], v[122:123] op_sel_hi:[1,0]
	v_exp_f32_e32 v124, v124
	v_exp_f32_e32 v126, v126
	v_exp_f32_e32 v125, v125
	v_exp_f32_e32 v127, v127
	global_store_dwordx4 v120, v[116:119], s[54:55]
	v_pk_mul_f32 v[104:105], v[108:109], v[104:105]
	v_pk_add_f32 v[120:121], v[126:127], 1.0 op_sel_hi:[1,0]
	v_pk_add_f32 v[118:119], v[124:125], 1.0 op_sel_hi:[1,0]
	v_rcp_f32_e32 v120, v120
	v_rcp_f32_e32 v121, v121
	v_rcp_f32_e32 v118, v118
	v_rcp_f32_e32 v119, v119
	v_mul_f32_e32 v116, v123, v123
	v_pk_mul_f32 v[108:109], v[116:117], v[120:121] op_sel_hi:[0,1]
	v_pk_mul_f32 v[120:121], v[100:101], v[122:123] op_sel_hi:[1,0]
	v_pk_mul_f32 v[110:111], v[116:117], v[118:119] op_sel_hi:[0,1]
	v_pk_mul_f32 v[118:119], v[102:103], v[122:123] op_sel_hi:[1,0]
	v_exp_f32_e32 v120, v120
	v_exp_f32_e32 v118, v118
	v_exp_f32_e32 v119, v119
	v_exp_f32_e32 v121, v121
	v_pk_mul_f32 v[106:107], v[106:107], v[110:111]
	v_pk_mul_f32 v[104:105], v[104:105], v[108:109]
	v_pk_add_f32 v[108:109], v[118:119], 1.0 op_sel_hi:[1,0]
	v_pk_add_f32 v[110:111], v[120:121], 1.0 op_sel_hi:[1,0]
	v_rcp_f32_e32 v108, v108
	v_rcp_f32_e32 v110, v110
	v_rcp_f32_e32 v111, v111
	v_rcp_f32_e32 v109, v109
	v_pk_mul_f32 v[98:99], v[102:103], v[98:99]
	v_pk_mul_f32 v[96:97], v[100:101], v[96:97]
	v_pk_mul_f32 v[100:101], v[116:117], v[110:111] op_sel_hi:[0,1]
	v_pk_mul_f32 v[102:103], v[116:117], v[108:109] op_sel_hi:[0,1]
	v_pk_mul_f32 v[102:103], v[98:99], v[102:103]
	v_pk_mul_f32 v[98:99], v[96:97], v[100:101]
	v_cvt_pk_bf16_f32 v96, v104, v105
	v_cvt_pk_bf16_f32 v97, v106, v107
	v_add_u32_e32 v100, s14, v140
	v_cvt_pk_bf16_f32 v98, v98, v99
	v_cvt_pk_bf16_f32 v99, v102, v103
	ds_read_b32 v103, v150 offset:128
	v_mad_u32_u24 v100, v100, s5, v114
	global_store_dwordx4 v100, v[96:99], s[54:55]
	s_waitcnt lgkmcnt(0)
	v_mul_f32_e32 v102, 0xbfb8aa3b, v103
	v_pk_mul_f32 v[104:105], v[94:95], v[102:103] op_sel_hi:[1,0]
	v_pk_mul_f32 v[106:107], v[92:93], v[102:103] op_sel_hi:[1,0]
	v_exp_f32_e32 v104, v104
	v_exp_f32_e32 v106, v106
	v_exp_f32_e32 v105, v105
	v_exp_f32_e32 v107, v107
	v_mul_f32_e32 v96, v103, v103
	v_pk_mul_f32 v[90:91], v[94:95], v[90:91]
	v_pk_add_f32 v[98:99], v[104:105], 1.0 op_sel_hi:[1,0]
	v_pk_add_f32 v[100:101], v[106:107], 1.0 op_sel_hi:[1,0]
	v_rcp_f32_e32 v98, v98
	v_rcp_f32_e32 v100, v100
	v_rcp_f32_e32 v101, v101
	v_rcp_f32_e32 v99, v99
	v_pk_mul_f32 v[88:89], v[92:93], v[88:89]
	v_pk_mul_f32 v[82:83], v[86:87], v[82:83]
	v_pk_mul_f32 v[92:93], v[96:97], v[100:101] op_sel_hi:[0,1]
	v_pk_mul_f32 v[94:95], v[96:97], v[98:99] op_sel_hi:[0,1]
	v_pk_mul_f32 v[98:99], v[86:87], v[102:103] op_sel_hi:[1,0]
	v_pk_mul_f32 v[100:101], v[84:85], v[102:103] op_sel_hi:[1,0]
	v_exp_f32_e32 v98, v98
	v_exp_f32_e32 v100, v100
	v_exp_f32_e32 v99, v99
	v_exp_f32_e32 v101, v101
	v_pk_mul_f32 v[90:91], v[90:91], v[94:95]
	v_pk_mul_f32 v[88:89], v[88:89], v[92:93]
	v_pk_add_f32 v[92:93], v[98:99], 1.0 op_sel_hi:[1,0]
	v_pk_add_f32 v[94:95], v[100:101], 1.0 op_sel_hi:[1,0]
	v_rcp_f32_e32 v92, v92
	v_rcp_f32_e32 v94, v94
	v_rcp_f32_e32 v95, v95
	v_rcp_f32_e32 v93, v93
	v_pk_mul_f32 v[80:81], v[84:85], v[80:81]
	v_pk_mul_f32 v[74:75], v[78:79], v[74:75]
	v_pk_mul_f32 v[84:85], v[96:97], v[94:95] op_sel_hi:[0,1]
	v_pk_mul_f32 v[86:87], v[96:97], v[92:93] op_sel_hi:[0,1]
	v_pk_mul_f32 v[86:87], v[82:83], v[86:87]
	v_pk_mul_f32 v[82:83], v[80:81], v[84:85]
	v_cvt_pk_bf16_f32 v80, v88, v89
	v_cvt_pk_bf16_f32 v81, v90, v91
	v_add_u32_e32 v84, s14, v141
	v_cvt_pk_bf16_f32 v82, v82, v83
	v_cvt_pk_bf16_f32 v83, v86, v87
	ds_read_b32 v87, v150 offset:192
	v_mad_u32_u24 v84, v84, s5, v114
	global_store_dwordx4 v84, v[80:83], s[54:55]
	s_waitcnt lgkmcnt(0)
; __device__ __forceinline__ u32x4 pack8(f32x4 a, f32x4 b) { u32x4 w; w.x = cvt_pk_bf16(a[0], a[1]); w.y = cvt_pk_bf16(a[2], a[3]); w.z = cvt_pk_bf16(b[0], b[1]); w.w = cvt_pk_bf16(b[2], b[3]); return w; }
;     __device__ __forceinline__ void operator()(const f32x4 (&acc)[2][2][4][2], const Unit& u, int wr, int wc, int fr, int fq) const {
;     ...
;             for (int m = 0; m < 4; ++m) { const int rl = rl0 + ai * HALF + m * 16; const float s = rs[u.ui * BM + rl];
;                 f32x4 h[2]; const float ns = -1.4426950408889634f * s, s2 = s * s;
; #pragma unroll
;                 for (int n = 0; n < 2; ++n) { const f32x4 g = acc[ai][0][m][n], up = acc[ai][1][m][n]; const f32x4 ea = g * ns;
;                     const f32x4 d = (f32x4){__builtin_amdgcn_exp2f(ea[0]), __builtin_amdgcn_exp2f(ea[1]), __builtin_amdgcn_exp2f(ea[2]), __builtin_amdgcn_exp2f(ea[3])} + 1.0f;
;                     const f32x4 r = (f32x4){__builtin_amdgcn_rcpf(d[0]), __builtin_amdgcn_rcpf(d[1]), __builtin_amdgcn_rcpf(d[2]), __builtin_amdgcn_rcpf(d[3])};
;                     h[n] = (g * up) * (r * s2); }
;                 st16(O + (size_t)(u.pm * BM + rl) * ldo + col0, pack8(h[0], h[1])); }
	v_mul_f32_e32 v86, 0xbfb8aa3b, v87
	v_pk_mul_f32 v[88:89], v[78:79], v[86:87] op_sel_hi:[1,0]
	v_pk_mul_f32 v[90:91], v[76:77], v[86:87] op_sel_hi:[1,0]
	v_exp_f32_e32 v88, v88
	v_exp_f32_e32 v90, v90
	v_exp_f32_e32 v89, v89
	v_exp_f32_e32 v91, v91
	v_mul_f32_e32 v80, v87, v87
	v_pk_mul_f32 v[72:73], v[76:77], v[72:73]
	v_pk_add_f32 v[82:83], v[88:89], 1.0 op_sel_hi:[1,0]
	v_pk_add_f32 v[84:85], v[90:91], 1.0 op_sel_hi:[1,0]
	v_rcp_f32_e32 v82, v82
	v_rcp_f32_e32 v84, v84
	v_rcp_f32_e32 v85, v85
	v_rcp_f32_e32 v83, v83
	v_pk_mul_f32 v[66:67], v[70:71], v[66:67]
	v_pk_mul_f32 v[64:65], v[68:69], v[64:65]
	v_pk_mul_f32 v[76:77], v[80:81], v[84:85] op_sel_hi:[0,1]
	v_pk_mul_f32 v[78:79], v[80:81], v[82:83] op_sel_hi:[0,1]
	v_pk_mul_f32 v[82:83], v[70:71], v[86:87] op_sel_hi:[1,0]
	v_pk_mul_f32 v[84:85], v[68:69], v[86:87] op_sel_hi:[1,0]
	v_exp_f32_e32 v82, v82
	v_exp_f32_e32 v84, v84
	v_exp_f32_e32 v83, v83
	v_exp_f32_e32 v85, v85
	v_pk_mul_f32 v[74:75], v[74:75], v[78:79]
	v_pk_mul_f32 v[72:73], v[72:73], v[76:77]
	v_pk_add_f32 v[76:77], v[82:83], 1.0 op_sel_hi:[1,0]
	v_pk_add_f32 v[78:79], v[84:85], 1.0 op_sel_hi:[1,0]
	v_rcp_f32_e32 v76, v76
	v_rcp_f32_e32 v78, v78
	v_rcp_f32_e32 v79, v79
	v_rcp_f32_e32 v77, v77
	v_pk_mul_f32 v[58:59], v[62:63], v[58:59]
	v_pk_mul_f32 v[56:57], v[60:61], v[56:57]
	v_pk_mul_f32 v[68:69], v[80:81], v[78:79] op_sel_hi:[0,1]
	v_pk_mul_f32 v[70:71], v[80:81], v[76:77] op_sel_hi:[0,1]
	v_pk_mul_f32 v[70:71], v[66:67], v[70:71]
	v_pk_mul_f32 v[66:67], v[64:65], v[68:69]
	v_cvt_pk_bf16_f32 v64, v72, v73
	v_cvt_pk_bf16_f32 v65, v74, v75
	v_add_u32_e32 v68, s14, v142
	v_cvt_pk_bf16_f32 v66, v66, v67
	v_cvt_pk_bf16_f32 v67, v70, v71
	ds_read_b32 v71, v150 offset:512
	v_mad_u32_u24 v68, v68, s5, v114
	global_store_dwordx4 v68, v[64:67], s[54:55]
	s_waitcnt lgkmcnt(0)
	v_mul_f32_e32 v70, 0xbfb8aa3b, v71
	v_pk_mul_f32 v[72:73], v[62:63], v[70:71] op_sel_hi:[1,0]
	v_pk_mul_f32 v[74:75], v[60:61], v[70:71] op_sel_hi:[1,0]
	v_exp_f32_e32 v72, v72
	v_exp_f32_e32 v74, v74
	v_exp_f32_e32 v73, v73
	v_exp_f32_e32 v75, v75
	v_mul_f32_e32 v64, v71, v71
	v_pk_mul_f32 v[50:51], v[54:55], v[50:51]
	v_pk_add_f32 v[66:67], v[72:73], 1.0 op_sel_hi:[1,0]
	v_pk_add_f32 v[68:69], v[74:75], 1.0 op_sel_hi:[1,0]
	v_rcp_f32_e32 v66, v66
	v_rcp_f32_e32 v68, v68
	v_rcp_f32_e32 v69, v69
	v_rcp_f32_e32 v67, v67
	v_pk_mul_f32 v[48:49], v[52:53], v[48:49]
	v_pk_mul_f32 v[42:43], v[46:47], v[42:43]
	v_pk_mul_f32 v[60:61], v[64:65], v[68:69] op_sel_hi:[0,1]
	v_pk_mul_f32 v[62:63], v[64:65], v[66:67] op_sel_hi:[0,1]
	v_pk_mul_f32 v[66:67], v[54:55], v[70:71] op_sel_hi:[1,0]
	v_pk_mul_f32 v[68:69], v[52:53], v[70:71] op_sel_hi:[1,0]
	v_exp_f32_e32 v66, v66
	v_exp_f32_e32 v68, v68
	v_exp_f32_e32 v67, v67
	v_exp_f32_e32 v69, v69
	v_pk_mul_f32 v[58:59], v[58:59], v[62:63]
	v_pk_mul_f32 v[56:57], v[56:57], v[60:61]
	v_pk_add_f32 v[60:61], v[66:67], 1.0 op_sel_hi:[1,0]
	v_pk_add_f32 v[62:63], v[68:69], 1.0 op_sel_hi:[1,0]
	v_rcp_f32_e32 v60, v60
	v_rcp_f32_e32 v62, v62
	v_rcp_f32_e32 v63, v63
	v_rcp_f32_e32 v61, v61
	v_pk_mul_f32 v[40:41], v[44:45], v[40:41]
	v_pk_mul_f32 v[34:35], v[38:39], v[34:35]
	v_pk_mul_f32 v[52:53], v[64:65], v[62:63] op_sel_hi:[0,1]
	v_pk_mul_f32 v[54:55], v[64:65], v[60:61] op_sel_hi:[0,1]
	v_pk_mul_f32 v[54:55], v[50:51], v[54:55]
	v_pk_mul_f32 v[50:51], v[48:49], v[52:53]
	v_cvt_pk_bf16_f32 v48, v56, v57
	v_cvt_pk_bf16_f32 v49, v58, v59
	v_add_u32_e32 v52, s14, v143
	v_cvt_pk_bf16_f32 v50, v50, v51
	v_cvt_pk_bf16_f32 v51, v54, v55
	ds_read_b32 v55, v150 offset:576
	v_mad_u32_u24 v52, v52, s5, v114
	global_store_dwordx4 v52, v[48:51], s[54:55]
	s_waitcnt lgkmcnt(0)
; __device__ __forceinline__ u32x4 pack8(f32x4 a, f32x4 b) { u32x4 w; w.x = cvt_pk_bf16(a[0], a[1]); w.y = cvt_pk_bf16(a[2], a[3]); w.z = cvt_pk_bf16(b[0], b[1]); w.w = cvt_pk_bf16(b[2], b[3]); return w; }
; #define PG8_BAR __builtin_amdgcn_s_barrier()
;     __device__ __forceinline__ void operator()(const f32x4 (&acc)[2][2][4][2], const Unit& u, int wr, int wc, int fr, int fq) const {
;     ...
;             for (int m = 0; m < 4; ++m) { const int rl = rl0 + ai * HALF + m * 16; const float s = rs[u.ui * BM + rl];
;                 f32x4 h[2]; const float ns = -1.4426950408889634f * s, s2 = s * s;
; #pragma unroll
;                 for (int n = 0; n < 2; ++n) { const f32x4 g = acc[ai][0][m][n], up = acc[ai][1][m][n]; const f32x4 ea = g * ns;
;                     const f32x4 d = (f32x4){__builtin_amdgcn_exp2f(ea[0]), __builtin_amdgcn_exp2f(ea[1]), __builtin_amdgcn_exp2f(ea[2]), __builtin_amdgcn_exp2f(ea[3])} + 1.0f;
;                     const f32x4 r = (f32x4){__builtin_amdgcn_rcpf(d[0]), __builtin_amdgcn_rcpf(d[1]), __builtin_amdgcn_rcpf(d[2]), __builtin_amdgcn_rcpf(d[3])};
;                     h[n] = (g * up) * (r * s2); }
;                 st16(O + (size_t)(u.pm * BM + rl) * ldo + col0, pack8(h[0], h[1])); }
; template <class Epi, class Sched, bool ALIGN_EPI = false, bool SP2 = false>
; __device__ __forceinline__ void gemm_phase(PG8_LAS unsigned char* lds, const Gemm g, const Sched& S, const Epi& E) {
;     ...
;         if constexpr (!Epi::AFTER_DRAIN) { E(acc, cur, wr, wc, fr, fq); S.done(cur); }
;         if (!has_next) break;
; #pragma unroll
;         for (int a = 0; a < 2; ++a)
; #pragma unroll
;             for (int b = 0; b < 2; ++b)
; #pragma unroll
;                 for (int m = 0; m < 4; ++m)
; #pragma unroll
;                     for (int n = 0; n < 2; ++n) acc[a][b][m][n] = (f32x4){0.f, 0.f, 0.f, 0.f};
;         cur = nxt; cA = nA; cB = nB; ++ui;
;         if constexpr (ALIGN_EPI) { if (wr == 1) PG8_BAR; }
	v_mul_f32_e32 v54, 0xbfb8aa3b, v55
	v_pk_mul_f32 v[56:57], v[46:47], v[54:55] op_sel_hi:[1,0]
	v_pk_mul_f32 v[58:59], v[44:45], v[54:55] op_sel_hi:[1,0]
	v_exp_f32_e32 v56, v56
	v_exp_f32_e32 v58, v58
	v_exp_f32_e32 v57, v57
	v_exp_f32_e32 v59, v59
	v_mul_f32_e32 v48, v55, v55
	v_pk_mul_f32 v[32:33], v[36:37], v[32:33]
	v_pk_add_f32 v[50:51], v[56:57], 1.0 op_sel_hi:[1,0]
	v_pk_add_f32 v[52:53], v[58:59], 1.0 op_sel_hi:[1,0]
	v_rcp_f32_e32 v50, v50
	v_rcp_f32_e32 v52, v52
	v_rcp_f32_e32 v53, v53
	v_rcp_f32_e32 v51, v51
	v_pk_mul_f32 v[26:27], v[30:31], v[26:27]
	v_pk_mul_f32 v[24:25], v[28:29], v[24:25]
	v_pk_mul_f32 v[44:45], v[48:49], v[52:53] op_sel_hi:[0,1]
	v_pk_mul_f32 v[46:47], v[48:49], v[50:51] op_sel_hi:[0,1]
	v_pk_mul_f32 v[50:51], v[38:39], v[54:55] op_sel_hi:[1,0]
	v_pk_mul_f32 v[52:53], v[36:37], v[54:55] op_sel_hi:[1,0]
	v_exp_f32_e32 v50, v50
	v_exp_f32_e32 v52, v52
	v_exp_f32_e32 v51, v51
	v_exp_f32_e32 v53, v53
	v_pk_mul_f32 v[42:43], v[42:43], v[46:47]
	v_pk_mul_f32 v[40:41], v[40:41], v[44:45]
	v_pk_add_f32 v[44:45], v[50:51], 1.0 op_sel_hi:[1,0]
	v_pk_add_f32 v[46:47], v[52:53], 1.0 op_sel_hi:[1,0]
	v_rcp_f32_e32 v44, v44
	v_rcp_f32_e32 v46, v46
	v_rcp_f32_e32 v47, v47
	v_rcp_f32_e32 v45, v45
	v_pk_mul_f32 v[18:19], v[22:23], v[18:19]
	v_pk_mul_f32 v[16:17], v[20:21], v[16:17]
	v_pk_mul_f32 v[36:37], v[48:49], v[46:47] op_sel_hi:[0,1]
	v_pk_mul_f32 v[38:39], v[48:49], v[44:45] op_sel_hi:[0,1]
	v_pk_mul_f32 v[38:39], v[34:35], v[38:39]
	v_pk_mul_f32 v[34:35], v[32:33], v[36:37]
	v_cvt_pk_bf16_f32 v32, v40, v41
	v_cvt_pk_bf16_f32 v33, v42, v43
	v_add_u32_e32 v36, s14, v144
	v_cvt_pk_bf16_f32 v34, v34, v35
	v_cvt_pk_bf16_f32 v35, v38, v39
	ds_read_b32 v39, v150 offset:640
	v_mad_u32_u24 v36, v36, s5, v114
	global_store_dwordx4 v36, v[32:35], s[54:55]
	s_waitcnt lgkmcnt(0)
	v_mul_f32_e32 v38, 0xbfb8aa3b, v39
	v_pk_mul_f32 v[40:41], v[30:31], v[38:39] op_sel_hi:[1,0]
	v_pk_mul_f32 v[42:43], v[28:29], v[38:39] op_sel_hi:[1,0]
	v_exp_f32_e32 v40, v40
	v_exp_f32_e32 v42, v42
	v_exp_f32_e32 v41, v41
	v_exp_f32_e32 v43, v43
	v_mul_f32_e32 v32, v39, v39
	v_pk_mul_f32 v[10:11], v[14:15], v[10:11]
	v_pk_add_f32 v[34:35], v[40:41], 1.0 op_sel_hi:[1,0]
	v_pk_add_f32 v[36:37], v[42:43], 1.0 op_sel_hi:[1,0]
	v_rcp_f32_e32 v34, v34
	v_rcp_f32_e32 v36, v36
	v_rcp_f32_e32 v37, v37
	v_rcp_f32_e32 v35, v35
	v_pk_mul_f32 v[8:9], v[12:13], v[8:9]
	v_pk_mul_f32 v[2:3], v[6:7], v[2:3]
	v_pk_mul_f32 v[28:29], v[32:33], v[36:37] op_sel_hi:[0,1]
	v_pk_mul_f32 v[30:31], v[32:33], v[34:35] op_sel_hi:[0,1]
	v_pk_mul_f32 v[34:35], v[22:23], v[38:39] op_sel_hi:[1,0]
	v_pk_mul_f32 v[36:37], v[20:21], v[38:39] op_sel_hi:[1,0]
	v_exp_f32_e32 v34, v34
	v_exp_f32_e32 v36, v36
	v_exp_f32_e32 v35, v35
	v_exp_f32_e32 v37, v37
	v_pk_mul_f32 v[26:27], v[26:27], v[30:31]
	v_pk_mul_f32 v[24:25], v[24:25], v[28:29]
	v_pk_add_f32 v[28:29], v[34:35], 1.0 op_sel_hi:[1,0]
	v_pk_add_f32 v[30:31], v[36:37], 1.0 op_sel_hi:[1,0]
	v_rcp_f32_e32 v28, v28
	v_rcp_f32_e32 v30, v30
	v_rcp_f32_e32 v31, v31
	v_rcp_f32_e32 v29, v29
	v_pk_mul_f32 v[0:1], v[4:5], v[0:1]
	s_andn2_b64 vcc, exec, s[6:7]
	v_pk_mul_f32 v[20:21], v[32:33], v[30:31] op_sel_hi:[0,1]
	v_pk_mul_f32 v[22:23], v[32:33], v[28:29] op_sel_hi:[0,1]
	v_pk_mul_f32 v[22:23], v[18:19], v[22:23]
	v_pk_mul_f32 v[18:19], v[16:17], v[20:21]
	v_cvt_pk_bf16_f32 v16, v24, v25
	v_cvt_pk_bf16_f32 v17, v26, v27
	v_add_u32_e32 v20, s14, v145
	v_cvt_pk_bf16_f32 v18, v18, v19
	v_cvt_pk_bf16_f32 v19, v22, v23
	ds_read_b32 v23, v150 offset:704
	v_mad_u32_u24 v20, v20, s5, v114
	global_store_dwordx4 v20, v[16:19], s[54:55]
	s_waitcnt lgkmcnt(0)
	v_mul_f32_e32 v22, 0xbfb8aa3b, v23
	v_pk_mul_f32 v[24:25], v[14:15], v[22:23] op_sel_hi:[1,0]
	v_pk_mul_f32 v[26:27], v[12:13], v[22:23] op_sel_hi:[1,0]
	v_exp_f32_e32 v24, v24
	v_exp_f32_e32 v26, v26
	v_exp_f32_e32 v25, v25
	v_exp_f32_e32 v27, v27
	v_mul_f32_e32 v16, v23, v23
	s_mov_b64 s[6:7], -1
	v_pk_add_f32 v[18:19], v[24:25], 1.0 op_sel_hi:[1,0]
	v_pk_add_f32 v[20:21], v[26:27], 1.0 op_sel_hi:[1,0]
	v_rcp_f32_e32 v18, v18
	v_rcp_f32_e32 v20, v20
	v_rcp_f32_e32 v21, v21
	v_rcp_f32_e32 v19, v19
	v_pk_mul_f32 v[12:13], v[16:17], v[20:21] op_sel_hi:[0,1]
	v_pk_mul_f32 v[14:15], v[16:17], v[18:19] op_sel_hi:[0,1]
	v_pk_mul_f32 v[18:19], v[6:7], v[22:23] op_sel_hi:[1,0]
	v_pk_mul_f32 v[20:21], v[4:5], v[22:23] op_sel_hi:[1,0]
	v_exp_f32_e32 v18, v18
	v_exp_f32_e32 v20, v20
	v_exp_f32_e32 v19, v19
	v_exp_f32_e32 v21, v21
	v_pk_mul_f32 v[10:11], v[10:11], v[14:15]
	v_pk_mul_f32 v[8:9], v[8:9], v[12:13]
	v_pk_add_f32 v[12:13], v[18:19], 1.0 op_sel_hi:[1,0]
	v_pk_add_f32 v[14:15], v[20:21], 1.0 op_sel_hi:[1,0]
	v_rcp_f32_e32 v12, v12
	v_rcp_f32_e32 v14, v14
	v_rcp_f32_e32 v15, v15
	v_rcp_f32_e32 v13, v13
	v_pk_mul_f32 v[4:5], v[16:17], v[14:15] op_sel_hi:[0,1]
	v_pk_mul_f32 v[6:7], v[16:17], v[12:13] op_sel_hi:[0,1]
	v_pk_mul_f32 v[6:7], v[2:3], v[6:7]
	v_pk_mul_f32 v[2:3], v[0:1], v[4:5]
	v_add_u32_e32 v0, s14, v146
	v_mad_u32_u24 v4, v0, s5, v114
	v_cvt_pk_bf16_f32 v0, v8, v9
	v_cvt_pk_bf16_f32 v1, v10, v11
	v_cvt_pk_bf16_f32 v2, v2, v3
	v_cvt_pk_bf16_f32 v3, v6, v7
	global_store_dwordx4 v4, v[0:3], s[54:55]
	s_cbranch_vccnz .LBB0_365
	s_andn2_b64 vcc, exec, s[12:13]
	s_cbranch_vccnz .LBB0_364
	s_barrier
	s_branch .LBB0_364
